# last down GEMM residual epilogue (f32 output) rewritten: bf16 source loads in flight instead of serialised round trips
# speedup vs baseline: 1.0030x; 1.0030x over previous
; __device__ __forceinline__ unsigned cvt_pk_bf16(float lo, float hi) { unsigned r; asm("v_cvt_pk_bf16_f32 %0, %1, %2" : "=v"(r) : "v"(lo), "v"(hi)); return r; }
;     __device__ __forceinline__ void operator()(const Acc& acc, const Unit& u, int wr, int wc, int fr, int fq) const {
;     ...
;         const int r0 = wr * 64 + fr, col0 = u.pn * 256 + wc * 32 + 8 * fq; const float* gp = gate + (size_t)mb * 9216 + col0;
;         f32x4 gv[2][2];
; #pragma unroll
;         for (int bj = 0; bj < 2; ++bj)
; #pragma unroll
;             for (int n = 0; n < 2; ++n) gv[bj][n] = *(const f32x4*)(gp + bj * 128 + n * 4) * f;
; #pragma unroll
;         for (int ai = 0; ai < 2; ++ai)
; #pragma unroll
;             for (int m = 0; m < 4; ++m) { const size_t off = (size_t)(r0 + ai * 128 + m * 16) * D + col0;
; #pragma unroll
;                 for (int bj = 0; bj < 2; ++bj) { const size_t o2 = off + bj * 128; f32x4 s0, s1;
;                     if (SRC32) { s0 = *(const f32x4*)(sp32 + o2); s1 = *(const f32x4*)(sp32 + o2 + 4); }
;                     else { const u32x4 q = *(const u32x4*)(sp16 + o2); s0 = (f32x4){bf2f(q.x & 0xffffu), bf2f(q.x >> 16), bf2f(q.y & 0xffffu), bf2f(q.y >> 16)}; s1 = (f32x4){bf2f(q.z & 0xffffu), bf2f(q.z >> 16), bf2f(q.w & 0xffffu), bf2f(q.w >> 16)}; }
;                     const f32x4 v0 = s0 + gv[bj][0] * acc[ai][bj][m][0], v1 = s1 + gv[bj][1] * acc[ai][bj][m][1];
;                     if (DST32) { *(f32x4*)(dp32 + o2) = v0; *(f32x4*)(dp32 + o2 + 4) = v1; }
;                     else { u32x4 w; w.x = cvt_pk_bf16(v0.x, v0.y); w.y = cvt_pk_bf16(v0.z, v0.w); w.z = cvt_pk_bf16(v1.x, v1.y); w.w = cvt_pk_bf16(v1.z, v1.w); *(u32x4*)(dp16 + o2) = w; } } }
.LBB0_1945:
	s_add_i32 s24, s45, 0xffffff80
	s_and_b64 s[22:23], s[22:23], exec
	s_cselect_b32 s24, s45, s24
	s_ashr_i32 s25, s24, 31
	s_lshl_b64 s[20:21], s[20:21], 2
	v_lshl_or_b32 v242, s46, 8, v167
	s_add_u32 s20, s37, s20
	s_addc_u32 s21, s38, s21
	v_lshlrev_b32_e32 v240, 2, v242
	global_load_dwordx4 v[156:159], v240, s[20:21]
	global_load_dwordx4 v[160:163], v240, s[20:21] offset:16
	global_load_dwordx4 v[172:175], v240, s[20:21] offset:512
	global_load_dwordx4 v[176:179], v240, s[20:21] offset:528
	s_lshl_b64 s[20:21], s[24:25], 19
	s_add_u32 s22, s72, s20
	s_addc_u32 s23, s73, s21
	s_lshl_b64 s[20:21], s[24:25], 20
	s_add_u32 s20, s86, s20
	s_addc_u32 s21, s87, s21
	v_add_lshl_u32 v241, v132, v242, 1
	global_load_dwordx4 v[180:183], v241, s[22:23]
	global_load_dwordx4 v[184:187], v241, s[22:23] offset:256
	v_add_lshl_u32 v240, v134, v242, 1
	global_load_dwordx4 v[188:191], v240, s[22:23]
	global_load_dwordx4 v[192:195], v240, s[22:23] offset:256
	v_add_lshl_u32 v241, v136, v242, 1
	global_load_dwordx4 v[196:199], v241, s[22:23]
	global_load_dwordx4 v[200:203], v241, s[22:23] offset:256
	v_add_lshl_u32 v240, v138, v242, 1
	global_load_dwordx4 v[204:207], v240, s[22:23]
	global_load_dwordx4 v[208:211], v240, s[22:23] offset:256
	v_add_lshl_u32 v241, v140, v242, 1
	global_load_dwordx4 v[212:215], v241, s[22:23]
	global_load_dwordx4 v[216:219], v241, s[22:23] offset:256
	v_add_lshl_u32 v240, v142, v242, 1
	global_load_dwordx4 v[220:223], v240, s[22:23]
	global_load_dwordx4 v[224:227], v240, s[22:23] offset:256
	s_waitcnt vmcnt(11)
	v_pk_mul_f32 v[156:157], v[156:157], 0.5 op_sel_hi:[1,0]
	v_pk_mul_f32 v[158:159], v[158:159], 0.5 op_sel_hi:[1,0]
	v_pk_mul_f32 v[160:161], v[160:161], 0.5 op_sel_hi:[1,0]
	v_pk_mul_f32 v[162:163], v[162:163], 0.5 op_sel_hi:[1,0]
	v_pk_mul_f32 v[172:173], v[172:173], 0.5 op_sel_hi:[1,0]
	v_pk_mul_f32 v[174:175], v[174:175], 0.5 op_sel_hi:[1,0]
	v_pk_mul_f32 v[176:177], v[176:177], 0.5 op_sel_hi:[1,0]
	v_pk_mul_f32 v[178:179], v[178:179], 0.5 op_sel_hi:[1,0]
	v_lshlrev_b32_e32 v236, 16, v180
	v_and_b32_e32 v237, 0xffff0000, v180
	v_lshlrev_b32_e32 v238, 16, v181
	v_and_b32_e32 v239, 0xffff0000, v181
	v_lshlrev_b32_e32 v180, 16, v182
	v_and_b32_e32 v181, 0xffff0000, v182
	v_lshlrev_b32_e32 v182, 16, v183
	v_and_b32_e32 v183, 0xffff0000, v183
	v_pk_fma_f32 v[124:125], v[124:125], v[156:157], v[236:237]
	v_pk_fma_f32 v[126:127], v[126:127], v[158:159], v[238:239]
	v_pk_fma_f32 v[120:121], v[120:121], v[160:161], v[180:181]
	v_pk_fma_f32 v[122:123], v[122:123], v[162:163], v[182:183]
	s_waitcnt vmcnt(10)
	v_lshlrev_b32_e32 v236, 16, v184
	v_and_b32_e32 v237, 0xffff0000, v184
	v_lshlrev_b32_e32 v238, 16, v185
	v_and_b32_e32 v239, 0xffff0000, v185
	v_lshlrev_b32_e32 v184, 16, v186
	v_and_b32_e32 v185, 0xffff0000, v186
	v_lshlrev_b32_e32 v186, 16, v187
	v_and_b32_e32 v187, 0xffff0000, v187
	v_pk_fma_f32 v[116:117], v[116:117], v[172:173], v[236:237]
	v_pk_fma_f32 v[118:119], v[118:119], v[174:175], v[238:239]
	v_pk_fma_f32 v[112:113], v[112:113], v[176:177], v[184:185]
	v_pk_fma_f32 v[114:115], v[114:115], v[178:179], v[186:187]
	s_waitcnt vmcnt(9)
	v_lshlrev_b32_e32 v236, 16, v188
	v_and_b32_e32 v237, 0xffff0000, v188
	v_lshlrev_b32_e32 v238, 16, v189
	v_and_b32_e32 v239, 0xffff0000, v189
	v_lshlrev_b32_e32 v188, 16, v190
	v_and_b32_e32 v189, 0xffff0000, v190
	v_lshlrev_b32_e32 v190, 16, v191
	v_and_b32_e32 v191, 0xffff0000, v191
	v_pk_fma_f32 v[108:109], v[108:109], v[156:157], v[236:237]
	v_pk_fma_f32 v[110:111], v[110:111], v[158:159], v[238:239]
	v_pk_fma_f32 v[104:105], v[104:105], v[160:161], v[188:189]
	v_pk_fma_f32 v[106:107], v[106:107], v[162:163], v[190:191]
	s_waitcnt vmcnt(8)
	v_lshlrev_b32_e32 v236, 16, v192
	v_and_b32_e32 v237, 0xffff0000, v192
	v_lshlrev_b32_e32 v238, 16, v193
	v_and_b32_e32 v239, 0xffff0000, v193
	v_lshlrev_b32_e32 v192, 16, v194
	v_and_b32_e32 v193, 0xffff0000, v194
	v_lshlrev_b32_e32 v194, 16, v195
	v_and_b32_e32 v195, 0xffff0000, v195
	v_pk_fma_f32 v[100:101], v[100:101], v[172:173], v[236:237]
	v_pk_fma_f32 v[102:103], v[102:103], v[174:175], v[238:239]
	v_pk_fma_f32 v[96:97], v[96:97], v[176:177], v[192:193]
	v_pk_fma_f32 v[98:99], v[98:99], v[178:179], v[194:195]
	v_add_lshl_u32 v241, v144, v242, 1
	global_load_dwordx4 v[180:183], v241, s[22:23]
	global_load_dwordx4 v[184:187], v241, s[22:23] offset:256
	v_add_lshl_u32 v240, v146, v242, 1
	global_load_dwordx4 v[188:191], v240, s[22:23]
	global_load_dwordx4 v[192:195], v240, s[22:23] offset:256
	s_waitcnt vmcnt(11)
	v_lshlrev_b32_e32 v236, 16, v196
	v_and_b32_e32 v237, 0xffff0000, v196
	v_lshlrev_b32_e32 v238, 16, v197
	v_and_b32_e32 v239, 0xffff0000, v197
	v_lshlrev_b32_e32 v196, 16, v198
	v_and_b32_e32 v197, 0xffff0000, v198
	v_lshlrev_b32_e32 v198, 16, v199
	v_and_b32_e32 v199, 0xffff0000, v199
	v_pk_fma_f32 v[92:93], v[92:93], v[156:157], v[236:237]
	v_pk_fma_f32 v[94:95], v[94:95], v[158:159], v[238:239]
	v_pk_fma_f32 v[88:89], v[88:89], v[160:161], v[196:197]
	v_pk_fma_f32 v[90:91], v[90:91], v[162:163], v[198:199]
	s_waitcnt vmcnt(10)
	v_lshlrev_b32_e32 v236, 16, v200
	v_and_b32_e32 v237, 0xffff0000, v200
	v_lshlrev_b32_e32 v238, 16, v201
	v_and_b32_e32 v239, 0xffff0000, v201
	v_lshlrev_b32_e32 v200, 16, v202
	v_and_b32_e32 v201, 0xffff0000, v202
	v_lshlrev_b32_e32 v202, 16, v203
	v_and_b32_e32 v203, 0xffff0000, v203
	v_pk_fma_f32 v[84:85], v[84:85], v[172:173], v[236:237]
	v_pk_fma_f32 v[86:87], v[86:87], v[174:175], v[238:239]
	v_pk_fma_f32 v[80:81], v[80:81], v[176:177], v[200:201]
	v_pk_fma_f32 v[82:83], v[82:83], v[178:179], v[202:203]
	s_waitcnt vmcnt(9)
;     __device__ __forceinline__ void operator()(const Acc& acc, const Unit& u, int wr, int wc, int fr, int fq) const {
;     ...
;             for (int m = 0; m < 4; ++m) { const size_t off = (size_t)(r0 + ai * 128 + m * 16) * D + col0;
; #pragma unroll
;                 for (int bj = 0; bj < 2; ++bj) { const size_t o2 = off + bj * 128; f32x4 s0, s1;
;                     if (SRC32) { s0 = *(const f32x4*)(sp32 + o2); s1 = *(const f32x4*)(sp32 + o2 + 4); }
;                     else { const u32x4 q = *(const u32x4*)(sp16 + o2); s0 = (f32x4){bf2f(q.x & 0xffffu), bf2f(q.x >> 16), bf2f(q.y & 0xffffu), bf2f(q.y >> 16)}; s1 = (f32x4){bf2f(q.z & 0xffffu), bf2f(q.z >> 16), bf2f(q.w & 0xffffu), bf2f(q.w >> 16)}; }
;                     const f32x4 v0 = s0 + gv[bj][0] * acc[ai][bj][m][0], v1 = s1 + gv[bj][1] * acc[ai][bj][m][1];
	v_lshlrev_b32_e32 v236, 16, v204
	v_and_b32_e32 v237, 0xffff0000, v204
	v_lshlrev_b32_e32 v238, 16, v205
	v_and_b32_e32 v239, 0xffff0000, v205
	v_lshlrev_b32_e32 v204, 16, v206
	v_and_b32_e32 v205, 0xffff0000, v206
	v_lshlrev_b32_e32 v206, 16, v207
	v_and_b32_e32 v207, 0xffff0000, v207
	v_pk_fma_f32 v[76:77], v[76:77], v[156:157], v[236:237]
	v_pk_fma_f32 v[78:79], v[78:79], v[158:159], v[238:239]
	v_pk_fma_f32 v[72:73], v[72:73], v[160:161], v[204:205]
	v_pk_fma_f32 v[74:75], v[74:75], v[162:163], v[206:207]
	s_waitcnt vmcnt(8)
	v_lshlrev_b32_e32 v236, 16, v208
	v_and_b32_e32 v237, 0xffff0000, v208
	v_lshlrev_b32_e32 v238, 16, v209
	v_and_b32_e32 v239, 0xffff0000, v209
	v_lshlrev_b32_e32 v208, 16, v210
	v_and_b32_e32 v209, 0xffff0000, v210
	v_lshlrev_b32_e32 v210, 16, v211
	v_and_b32_e32 v211, 0xffff0000, v211
	v_pk_fma_f32 v[68:69], v[68:69], v[172:173], v[236:237]
	v_pk_fma_f32 v[70:71], v[70:71], v[174:175], v[238:239]
	v_pk_fma_f32 v[64:65], v[64:65], v[176:177], v[208:209]
	v_pk_fma_f32 v[66:67], v[66:67], v[178:179], v[210:211]
	s_waitcnt vmcnt(7)
	v_lshlrev_b32_e32 v236, 16, v212
	v_and_b32_e32 v237, 0xffff0000, v212
	v_lshlrev_b32_e32 v238, 16, v213
	v_and_b32_e32 v239, 0xffff0000, v213
	v_lshlrev_b32_e32 v212, 16, v214
	v_and_b32_e32 v213, 0xffff0000, v214
	v_lshlrev_b32_e32 v214, 16, v215
	v_and_b32_e32 v215, 0xffff0000, v215
	v_pk_fma_f32 v[60:61], v[60:61], v[156:157], v[236:237]
	v_pk_fma_f32 v[62:63], v[62:63], v[158:159], v[238:239]
	v_pk_fma_f32 v[56:57], v[56:57], v[160:161], v[212:213]
	v_pk_fma_f32 v[58:59], v[58:59], v[162:163], v[214:215]
	s_waitcnt vmcnt(6)
	v_lshlrev_b32_e32 v236, 16, v216
	v_and_b32_e32 v237, 0xffff0000, v216
	v_lshlrev_b32_e32 v238, 16, v217
	v_and_b32_e32 v239, 0xffff0000, v217
	v_lshlrev_b32_e32 v216, 16, v218
	v_and_b32_e32 v217, 0xffff0000, v218
	v_lshlrev_b32_e32 v218, 16, v219
	v_and_b32_e32 v219, 0xffff0000, v219
	v_pk_fma_f32 v[52:53], v[52:53], v[172:173], v[236:237]
	v_pk_fma_f32 v[54:55], v[54:55], v[174:175], v[238:239]
	v_pk_fma_f32 v[48:49], v[48:49], v[176:177], v[216:217]
	v_pk_fma_f32 v[50:51], v[50:51], v[178:179], v[218:219]
	s_waitcnt vmcnt(5)
	v_lshlrev_b32_e32 v236, 16, v220
	v_and_b32_e32 v237, 0xffff0000, v220
	v_lshlrev_b32_e32 v238, 16, v221
	v_and_b32_e32 v239, 0xffff0000, v221
	v_lshlrev_b32_e32 v220, 16, v222
	v_and_b32_e32 v221, 0xffff0000, v222
	v_lshlrev_b32_e32 v222, 16, v223
	v_and_b32_e32 v223, 0xffff0000, v223
	v_pk_fma_f32 v[44:45], v[44:45], v[156:157], v[236:237]
	v_pk_fma_f32 v[46:47], v[46:47], v[158:159], v[238:239]
	v_pk_fma_f32 v[40:41], v[40:41], v[160:161], v[220:221]
	v_pk_fma_f32 v[42:43], v[42:43], v[162:163], v[222:223]
	s_waitcnt vmcnt(4)
	v_lshlrev_b32_e32 v236, 16, v224
	v_and_b32_e32 v237, 0xffff0000, v224
	v_lshlrev_b32_e32 v238, 16, v225
	v_and_b32_e32 v239, 0xffff0000, v225
	v_lshlrev_b32_e32 v224, 16, v226
	v_and_b32_e32 v225, 0xffff0000, v226
	v_lshlrev_b32_e32 v226, 16, v227
	v_and_b32_e32 v227, 0xffff0000, v227
	v_pk_fma_f32 v[36:37], v[36:37], v[172:173], v[236:237]
	v_pk_fma_f32 v[38:39], v[38:39], v[174:175], v[238:239]
	v_pk_fma_f32 v[32:33], v[32:33], v[176:177], v[224:225]
	v_pk_fma_f32 v[34:35], v[34:35], v[178:179], v[226:227]
	s_waitcnt vmcnt(3)
	v_lshlrev_b32_e32 v236, 16, v180
	v_and_b32_e32 v237, 0xffff0000, v180
	v_lshlrev_b32_e32 v238, 16, v181
	v_and_b32_e32 v239, 0xffff0000, v181
	v_lshlrev_b32_e32 v180, 16, v182
	v_and_b32_e32 v181, 0xffff0000, v182
	v_lshlrev_b32_e32 v182, 16, v183
	v_and_b32_e32 v183, 0xffff0000, v183
	v_pk_fma_f32 v[28:29], v[28:29], v[156:157], v[236:237]
	v_pk_fma_f32 v[30:31], v[30:31], v[158:159], v[238:239]
	v_pk_fma_f32 v[24:25], v[24:25], v[160:161], v[180:181]
	v_pk_fma_f32 v[26:27], v[26:27], v[162:163], v[182:183]
	s_waitcnt vmcnt(2)
; __device__ __forceinline__ unsigned cvt_pk_bf16(float lo, float hi) { unsigned r; asm("v_cvt_pk_bf16_f32 %0, %1, %2" : "=v"(r) : "v"(lo), "v"(hi)); return r; }
; #define PG8_BAR __builtin_amdgcn_s_barrier()
; template <class Epi, class Sched, bool SWAPD = false>
; __device__ __forceinline__ void gemm_phase(LAS unsigned char* lds, const Gemm g, const Sched& S, const Epi& E) {
;     ...
;         if (!has_next) break;
; #pragma unroll
;         for (int a = 0; a < 2; ++a)
; #pragma unroll
;             for (int b = 0; b < 2; ++b)
; #pragma unroll
;                 for (int m = 0; m < 4; ++m)
; #pragma unroll
;                     for (int n = 0; n < 2; ++n) acc[a][b][m][n] = (f32x4){0.f, 0.f, 0.f, 0.f};
;         cur = nxt; cA = nA; cB = nB; ++ui;
;         if (wr == 1) PG8_BAR;
;     __device__ __forceinline__ void operator()(const Acc& acc, const Unit& u, int wr, int wc, int fr, int fq) const {
;     ...
;             for (int m = 0; m < 4; ++m) { const size_t off = (size_t)(r0 + ai * 128 + m * 16) * D + col0;
; #pragma unroll
;                 for (int bj = 0; bj < 2; ++bj) { const size_t o2 = off + bj * 128; f32x4 s0, s1;
;                     if (SRC32) { s0 = *(const f32x4*)(sp32 + o2); s1 = *(const f32x4*)(sp32 + o2 + 4); }
;                     else { const u32x4 q = *(const u32x4*)(sp16 + o2); s0 = (f32x4){bf2f(q.x & 0xffffu), bf2f(q.x >> 16), bf2f(q.y & 0xffffu), bf2f(q.y >> 16)}; s1 = (f32x4){bf2f(q.z & 0xffffu), bf2f(q.z >> 16), bf2f(q.w & 0xffffu), bf2f(q.w >> 16)}; }
;                     const f32x4 v0 = s0 + gv[bj][0] * acc[ai][bj][m][0], v1 = s1 + gv[bj][1] * acc[ai][bj][m][1];
;                     if (DST32) { *(f32x4*)(dp32 + o2) = v0; *(f32x4*)(dp32 + o2 + 4) = v1; }
;                     else { u32x4 w; w.x = cvt_pk_bf16(v0.x, v0.y); w.y = cvt_pk_bf16(v0.z, v0.w); w.z = cvt_pk_bf16(v1.x, v1.y); w.w = cvt_pk_bf16(v1.z, v1.w); *(u32x4*)(dp16 + o2) = w; } } }
	v_lshlrev_b32_e32 v236, 16, v184
	v_and_b32_e32 v237, 0xffff0000, v184
	v_lshlrev_b32_e32 v238, 16, v185
	v_and_b32_e32 v239, 0xffff0000, v185
	v_lshlrev_b32_e32 v184, 16, v186
	v_and_b32_e32 v185, 0xffff0000, v186
	v_lshlrev_b32_e32 v186, 16, v187
	v_and_b32_e32 v187, 0xffff0000, v187
	v_pk_fma_f32 v[20:21], v[20:21], v[172:173], v[236:237]
	v_pk_fma_f32 v[22:23], v[22:23], v[174:175], v[238:239]
	v_pk_fma_f32 v[16:17], v[16:17], v[176:177], v[184:185]
	v_pk_fma_f32 v[18:19], v[18:19], v[178:179], v[186:187]
	s_waitcnt vmcnt(1)
	v_lshlrev_b32_e32 v236, 16, v188
	v_and_b32_e32 v237, 0xffff0000, v188
	v_lshlrev_b32_e32 v238, 16, v189
	v_and_b32_e32 v239, 0xffff0000, v189
	v_lshlrev_b32_e32 v188, 16, v190
	v_and_b32_e32 v189, 0xffff0000, v190
	v_lshlrev_b32_e32 v190, 16, v191
	v_and_b32_e32 v191, 0xffff0000, v191
	v_pk_fma_f32 v[12:13], v[12:13], v[156:157], v[236:237]
	v_pk_fma_f32 v[14:15], v[14:15], v[158:159], v[238:239]
	v_pk_fma_f32 v[8:9], v[8:9], v[160:161], v[188:189]
	v_pk_fma_f32 v[10:11], v[10:11], v[162:163], v[190:191]
	s_waitcnt vmcnt(0)
	v_lshlrev_b32_e32 v236, 16, v192
	v_and_b32_e32 v237, 0xffff0000, v192
	v_lshlrev_b32_e32 v238, 16, v193
	v_and_b32_e32 v239, 0xffff0000, v193
	v_lshlrev_b32_e32 v192, 16, v194
	v_and_b32_e32 v193, 0xffff0000, v194
	v_lshlrev_b32_e32 v194, 16, v195
	v_and_b32_e32 v195, 0xffff0000, v195
	v_pk_fma_f32 v[4:5], v[4:5], v[172:173], v[236:237]
	v_pk_fma_f32 v[6:7], v[6:7], v[174:175], v[238:239]
	v_pk_fma_f32 v[0:1], v[0:1], v[176:177], v[192:193]
	v_pk_fma_f32 v[2:3], v[2:3], v[178:179], v[194:195]
	v_add_lshl_u32 v240, v132, v242, 2
	global_store_dwordx4 v240, v[124:127], s[20:21]
	global_store_dwordx4 v240, v[120:123], s[20:21] offset:16
	global_store_dwordx4 v240, v[116:119], s[20:21] offset:512
	global_store_dwordx4 v240, v[112:115], s[20:21] offset:528
	v_add_lshl_u32 v241, v134, v242, 2
	global_store_dwordx4 v241, v[108:111], s[20:21]
	global_store_dwordx4 v241, v[104:107], s[20:21] offset:16
	global_store_dwordx4 v241, v[100:103], s[20:21] offset:512
	global_store_dwordx4 v241, v[96:99], s[20:21] offset:528
	v_add_lshl_u32 v240, v136, v242, 2
	global_store_dwordx4 v240, v[92:95], s[20:21]
	global_store_dwordx4 v240, v[88:91], s[20:21] offset:16
	global_store_dwordx4 v240, v[84:87], s[20:21] offset:512
	global_store_dwordx4 v240, v[80:83], s[20:21] offset:528
	v_add_lshl_u32 v241, v138, v242, 2
	global_store_dwordx4 v241, v[76:79], s[20:21]
	global_store_dwordx4 v241, v[72:75], s[20:21] offset:16
	global_store_dwordx4 v241, v[68:71], s[20:21] offset:512
	global_store_dwordx4 v241, v[64:67], s[20:21] offset:528
	v_add_lshl_u32 v240, v140, v242, 2
	global_store_dwordx4 v240, v[60:63], s[20:21]
	global_store_dwordx4 v240, v[56:59], s[20:21] offset:16
	global_store_dwordx4 v240, v[52:55], s[20:21] offset:512
	global_store_dwordx4 v240, v[48:51], s[20:21] offset:528
	v_add_lshl_u32 v241, v142, v242, 2
	global_store_dwordx4 v241, v[44:47], s[20:21]
	global_store_dwordx4 v241, v[40:43], s[20:21] offset:16
	global_store_dwordx4 v241, v[36:39], s[20:21] offset:512
	global_store_dwordx4 v241, v[32:35], s[20:21] offset:528
	v_add_lshl_u32 v240, v144, v242, 2
	global_store_dwordx4 v240, v[28:31], s[20:21]
	global_store_dwordx4 v240, v[24:27], s[20:21] offset:16
	global_store_dwordx4 v240, v[20:23], s[20:21] offset:512
	global_store_dwordx4 v240, v[16:19], s[20:21] offset:528
	v_add_lshl_u32 v241, v146, v242, 2
	global_store_dwordx4 v241, v[12:15], s[20:21]
	global_store_dwordx4 v241, v[8:11], s[20:21] offset:16
	global_store_dwordx4 v241, v[4:7], s[20:21] offset:512
	global_store_dwordx4 v241, v[0:3], s[20:21] offset:528
	s_andn2_b64 vcc, exec, s[0:1]
	s_mov_b64 s[0:1], -1
	s_cbranch_vccnz .LBB0_1932
	s_andn2_b64 vcc, exec, s[4:5]
	s_cbranch_vccnz .LBB0_1931
	s_barrier
	s_branch .LBB0_1931
